# in-odd GEMM phase: half of the workgroups (id bit 3) start 3.4 us late so the store-only epilogue bursts of the two halves do not coincide
# baseline (speedup 1.0000x reference)
.LBB0_1233:
	s_andn2_b64 vcc, exec, s[2:3]
	s_cbranch_vccnz .LBB0_1341
	v_readlane_b32 s98, v254, 1
	s_bitcmp1_b32 s98, 3
	s_cbranch_scc0 .Lstg_c7
	s_sleep 127
.Lstg_c7:
	s_waitcnt vmcnt(0)
	v_bfe_i32 v3, v200, 27, 1
	v_lshlrev_b32_e32 v2, 4, v200
	v_lshrrev_b32_e32 v3, 22, v3
	v_add_u32_e32 v3, v2, v3
	v_and_b32_e32 v3, 0xfffffc00, v3
	v_sub_u32_e32 v3, v2, v3
	v_lshrrev_b32_e32 v4, 4, v3
	v_bitop3_b32 v3, v4, v3, 32 bitop3:0x6c
	v_ashrrev_i32_e32 v5, 31, v3
	v_ashrrev_i32_e32 v0, 31, v200
	v_lshrrev_b32_e32 v5, 26, v5
	v_lshrrev_b32_e32 v0, 26, v0
	v_add_u32_e32 v5, v3, v5
	v_add_u32_e32 v0, v200, v0
	v_ashrrev_i32_e32 v10, 6, v5
	v_and_b32_e32 v5, 0xc0, v5
	v_ashrrev_i32_e32 v0, 6, v0
	v_sub_u32_e32 v3, v3, v5
	v_lshlrev_b32_e32 v4, 3, v0
	v_lshlrev_b32_e32 v6, 5, v0
	v_ashrrev_i16_sdwa v3, v193, sext(v3) dst_sel:DWORD dst_unused:UNUSED_PAD src0_sel:DWORD src1_sel:BYTE_0
	v_and_b32_e32 v4, 0x1ffff0, v4
	v_and_b32_e32 v6, 32, v6
	v_bfe_i32 v11, v3, 0, 16
	v_add_u32_e32 v3, v6, v11
	v_add_lshl_u32 v4, v10, v4, 11
	v_add_u32_e32 v2, 0x2000, v2
	v_lshl_add_u32 v130, v3, 1, v4
	v_ashrrev_i32_e32 v3, 31, v2
	v_lshrrev_b32_e32 v3, 22, v3
	v_add_u32_e32 v3, v2, v3
	v_ashrrev_i32_e32 v12, 10, v3
	v_mul_i32_i24_e32 v3, 0x400, v12
	v_sub_u32_e32 v2, v2, v3
	v_lshrrev_b32_e32 v3, 4, v2
	v_bitop3_b32 v2, v3, v2, 32 bitop3:0x6c
	s_ashr_i32 s7, s19, 6
	s_waitcnt lgkmcnt(0)
	s_ashr_i32 s45, s44, 31
	s_ashr_i32 s43, s42, 31
	s_ashr_i32 s4, s19, 8
	v_ashrrev_i32_e32 v4, 31, v2
	s_lshl_b32 s6, s7, 10
	s_lshl_b64 s[0:1], s[44:45], 19
	s_lshl_b64 s[2:3], s[42:43], 19
	v_lshrrev_b32_e32 v4, 26, v4
	s_add_u32 s34, s96, s2
	s_mov_b32 s79, s37
	v_add_u32_e32 v4, v2, v4
	s_addc_u32 s35, s65, s3
	s_add_i32 s37, s36, 0x10000
	v_ashrrev_i32_e32 v13, 6, v4
	v_and_b32_e32 v4, 0xc0, v4
	s_add_i32 s62, s37, s6
	v_sub_u32_e32 v2, v2, v4
	s_add_i32 s63, s62, 0x2000
	v_lshlrev_b32_e32 v3, 3, v12
	v_lshlrev_b32_e32 v5, 5, v12
	v_ashrrev_i16_sdwa v2, v193, sext(v2) dst_sel:DWORD dst_unused:UNUSED_PAD src0_sel:DWORD src1_sel:BYTE_0
	s_add_u32 s20, s22, s0
	v_and_b32_e32 v3, 0x1ffff0, v3
	v_and_b32_e32 v5, 32, v5
	v_bfe_i32 v14, v2, 0, 16
	s_addc_u32 s21, s23, s1
	s_add_i32 s66, s36, s6
	v_add_u32_e32 v2, v5, v14
	v_add_lshl_u32 v3, v13, v3, 11
	s_mov_b32 m0, s62
	s_add_i32 s67, s66, 0x2000
	v_lshl_add_u32 v132, v2, 1, v3
	global_load_lds_dwordx4 v130, s[34:35]
	s_mov_b32 m0, s63
	s_add_u32 s0, s34, 0x40000
	global_load_lds_dwordx4 v132, s[34:35]
	s_mov_b32 m0, s66
	s_addc_u32 s1, s35, 0
	s_add_i32 s26, s36, 0x14000
	global_load_lds_dwordx4 v130, s[20:21]
	s_mov_b32 m0, s67
	s_add_i32 s68, s26, s6
	global_load_lds_dwordx4 v132, s[20:21]
	s_mov_b32 m0, s68
	s_add_i32 s28, s68, 0x2000
	global_load_lds_dwordx4 v130, s[0:1]
	s_mov_b32 m0, s28
	v_mov_b32_e32 v131, v1
	global_load_lds_dwordx4 v132, s[0:1]
	s_add_u32 s0, s20, 0x40000
	s_addc_u32 s1, s21, 0
	s_add_i32 s30, s66, 0x4000
	s_mov_b32 m0, s30
	s_add_i32 s69, s66, 0x6000
	global_load_lds_dwordx4 v130, s[0:1]
	s_mov_b32 m0, s69
	v_mov_b32_e32 v133, v1
	global_load_lds_dwordx4 v132, s[0:1]
	s_mov_b32 s16, s65
	s_mov_b32 s78, s36
	v_lshl_add_u64 v[8:9], s[34:35], 0, v[130:131]
	v_lshl_add_u64 v[6:7], s[34:35], 0, v[132:133]
	v_lshl_add_u64 v[4:5], s[20:21], 0, v[130:131]
	s_cmp_lg_u32 s4, 1
	v_lshl_add_u64 v[2:3], s[20:21], 0, v[132:133]
	s_cbranch_scc1 .LBB0_1236
	s_barrier
